# context-row mini-GEMM: two 64-wide k-chunks in flight per wave (32 fragment loads up front, second chunk via immediate offsets, aliased/late destinations), counted waits
# speedup vs baseline: 1.0099x; 1.0004x over previous
; template <int MODE> __device__ __forceinline__ void mini_gemm_ctx(const u16* A, const u16* Bt, int N, int K, u16* Ob, int ldo, int act, const float* gate, LAS unsigned char* L, int vb, int G_, int wave, int lane) {
;     ...
;         const u16* ap = A + (size_t)(r0 + fr) * K + wave * kslice + 8 * fq; const u16* bp = Bt + (size_t)(n0 + fr) * K + wave * kslice + 8 * fq;
; #pragma unroll 1
;         for (int kc = 0; kc < kslice; kc += 64) {
;             mbf16x8 fa[4][2], fb[4][2];
; #pragma unroll
;             for (int s = 0; s < 2; ++s)
; #pragma unroll
;                 for (int q = 0; q < 4; ++q) { fa[q][s] = *(const mbf16x8*)(ap + (size_t)(16 * q) * K + kc + 32 * s); fb[q][s] = *(const mbf16x8*)(bp + (size_t)(16 * q) * K + kc + 32 * s); }
; #pragma unroll
;             for (int s = 0; s < 2; ++s)
; #pragma unroll
;                 for (int mi = 0; mi < 4; ++mi)
; #pragma unroll
;                     for (int ni = 0; ni < 4; ++ni) acc[mi][ni] = __builtin_amdgcn_mfma_f32_16x16x32_bf16(fa[mi][s], fb[ni][s], acc[mi][ni], 0, 0, 0);
;         }
.LBB0_383:
	v_lshl_add_u64 v[120:121], v[80:81], 0, v[66:67]
	v_lshl_add_u64 v[104:105], v[68:69], 0, v[66:67]
	v_lshl_add_u64 v[106:107], v[82:83], 0, v[66:67]
	v_lshl_add_u64 v[108:109], v[76:77], 0, v[66:67]
	v_lshl_add_u64 v[110:111], v[70:71], 0, v[66:67]
	v_add_co_u32_e32 v124, vcc, s2, v104
	v_add_co_u32_e64 v126, s[44:45], s2, v106
	v_add_co_u32_e64 v128, s[46:47], s2, v108
	v_add_co_u32_e64 v130, s[50:51], s2, v110
	v_addc_co_u32_e32 v125, vcc, 0, v105, vcc
	v_addc_co_u32_e64 v127, vcc, 0, v107, s[44:45]
	v_addc_co_u32_e64 v129, vcc, 0, v109, s[46:47]
	v_addc_co_u32_e64 v131, vcc, 0, v111, s[50:51]
	v_lshl_add_u64 v[122:123], v[72:73], 0, v[66:67]
	v_lshl_add_u64 v[132:133], v[74:75], 0, v[66:67]
	v_lshl_add_u64 v[134:135], v[78:79], 0, v[66:67]
	global_load_dwordx4 v[136:139], v[120:121], off offset:-64
	global_load_dwordx4 v[140:143], v[124:125], off
	global_load_dwordx4 v[144:147], v[126:127], off
	global_load_dwordx4 v[148:151], v[128:129], off
	global_load_dwordx4 v[152:155], v[130:131], off
	global_load_dwordx4 v[156:159], v[122:123], off
	global_load_dwordx4 v[160:163], v[132:133], off
	global_load_dwordx4 v[164:167], v[134:135], off
	global_load_dwordx4 v[168:171], v[120:121], off
	global_load_dwordx4 v[172:175], v[124:125], off offset:64
	global_load_dwordx4 v[176:179], v[126:127], off offset:64
	global_load_dwordx4 v[180:183], v[128:129], off offset:64
	global_load_dwordx4 v[184:187], v[130:131], off offset:64
	global_load_dwordx4 v[188:191], v[122:123], off offset:64
	global_load_dwordx4 v[192:195], v[132:133], off offset:64
	global_load_dwordx4 v[196:199], v[134:135], off offset:64
	global_load_dwordx4 v[100:103], v[120:121], off offset:64
	global_load_dwordx4 v[104:107], v[124:125], off offset:128
	global_load_dwordx4 v[108:111], v[126:127], off offset:128
	global_load_dwordx4 v[112:115], v[128:129], off offset:128
	global_load_dwordx4 v[116:119], v[130:131], off offset:128
	global_load_dwordx4 v[200:203], v[122:123], off offset:128
	global_load_dwordx4 v[210:213], v[132:133], off offset:128
	global_load_dwordx4 v[226:229], v[134:135], off offset:128
	global_load_dwordx4 v[230:233], v[124:125], off offset:192
	global_load_dwordx4 v[234:237], v[126:127], off offset:192
	global_load_dwordx4 v[240:243], v[128:129], off offset:192
	global_load_dwordx4 v[244:247], v[130:131], off offset:192
	global_load_dwordx4 v[128:131], v[120:121], off offset:128
	global_load_dwordx4 v[124:127], v[122:123], off offset:192
	global_load_dwordx4 v[120:123], v[132:133], off offset:192
	s_add_i32 s78, s78, 128
	s_lshl_b64 s[100:101], s[24:25], 1
	v_lshl_add_u64 v[68:69], v[68:69], 0, s[100:101]
	v_lshl_add_u64 v[70:71], v[70:71], 0, s[100:101]
	v_lshl_add_u64 v[72:73], v[72:73], 0, s[100:101]
	v_lshl_add_u64 v[74:75], v[74:75], 0, s[100:101]
	v_lshl_add_u64 v[76:77], v[76:77], 0, s[100:101]
	v_lshl_add_u64 v[78:79], v[78:79], 0, s[100:101]
	v_lshl_add_u64 v[80:81], v[80:81], 0, s[100:101]
	v_lshl_add_u64 v[82:83], v[82:83], 0, s[100:101]
	s_cmp_ge_u32 s78, s80
	s_waitcnt vmcnt(26)
	v_mfma_f32_16x16x32_bf16 v[2:5], v[136:139], v[140:143], v[2:5]
	v_mfma_f32_16x16x32_bf16 v[6:9], v[136:139], v[144:147], v[6:9]
	v_mfma_f32_16x16x32_bf16 v[10:13], v[136:139], v[148:151], v[10:13]
	v_mfma_f32_16x16x32_bf16 v[14:17], v[136:139], v[152:155], v[14:17]
	global_load_dwordx4 v[136:139], v[134:135], off offset:192
	s_waitcnt vmcnt(26)
	v_mfma_f32_16x16x32_bf16 v[18:21], v[156:159], v[140:143], v[18:21]
	v_mfma_f32_16x16x32_bf16 v[22:25], v[156:159], v[144:147], v[22:25]
	v_mfma_f32_16x16x32_bf16 v[26:29], v[156:159], v[148:151], v[26:29]
	v_mfma_f32_16x16x32_bf16 v[30:33], v[156:159], v[152:155], v[30:33]
	s_waitcnt vmcnt(25)
	v_mfma_f32_16x16x32_bf16 v[34:37], v[160:163], v[140:143], v[34:37]
	v_mfma_f32_16x16x32_bf16 v[38:41], v[160:163], v[144:147], v[38:41]
	v_mfma_f32_16x16x32_bf16 v[42:45], v[160:163], v[148:151], v[42:45]
	v_mfma_f32_16x16x32_bf16 v[46:49], v[160:163], v[152:155], v[46:49]
	s_waitcnt vmcnt(24)
	v_mfma_f32_16x16x32_bf16 v[50:53], v[164:167], v[140:143], v[50:53]
	v_mfma_f32_16x16x32_bf16 v[54:57], v[164:167], v[144:147], v[54:57]
	v_mfma_f32_16x16x32_bf16 v[62:65], v[164:167], v[148:151], v[62:65]
	v_mfma_f32_16x16x32_bf16 v[58:61], v[164:167], v[152:155], v[58:61]
	s_waitcnt vmcnt(19)
	v_mfma_f32_16x16x32_bf16 v[2:5], v[168:171], v[172:175], v[2:5]
	v_mfma_f32_16x16x32_bf16 v[6:9], v[168:171], v[176:179], v[6:9]
	v_mfma_f32_16x16x32_bf16 v[10:13], v[168:171], v[180:183], v[10:13]
	v_mfma_f32_16x16x32_bf16 v[14:17], v[168:171], v[184:187], v[14:17]
	s_waitcnt vmcnt(18)
	v_mfma_f32_16x16x32_bf16 v[18:21], v[188:191], v[172:175], v[18:21]
	v_mfma_f32_16x16x32_bf16 v[22:25], v[188:191], v[176:179], v[22:25]
	v_mfma_f32_16x16x32_bf16 v[26:29], v[188:191], v[180:183], v[26:29]
	v_mfma_f32_16x16x32_bf16 v[30:33], v[188:191], v[184:187], v[30:33]
	s_waitcnt vmcnt(17)
	v_mfma_f32_16x16x32_bf16 v[34:37], v[192:195], v[172:175], v[34:37]
	v_mfma_f32_16x16x32_bf16 v[38:41], v[192:195], v[176:179], v[38:41]
	v_mfma_f32_16x16x32_bf16 v[42:45], v[192:195], v[180:183], v[42:45]
	v_mfma_f32_16x16x32_bf16 v[46:49], v[192:195], v[184:187], v[46:49]
	s_waitcnt vmcnt(16)
	v_mfma_f32_16x16x32_bf16 v[50:53], v[196:199], v[172:175], v[50:53]
	v_mfma_f32_16x16x32_bf16 v[54:57], v[196:199], v[176:179], v[54:57]
	v_mfma_f32_16x16x32_bf16 v[62:65], v[196:199], v[180:183], v[62:65]
	v_mfma_f32_16x16x32_bf16 v[58:61], v[196:199], v[184:187], v[58:61]
	s_waitcnt vmcnt(11)
; __device__ __forceinline__ unsigned pk2(float lo, float hi) { return pg8::cvt_pk_bf16(lo, hi); }
; template <int MODE> __device__ __forceinline__ void mini_gemm_ctx(const u16* A, const u16* Bt, int N, int K, u16* Ob, int ldo, int act, const float* gate, LAS unsigned char* L, int vb, int G_, int wave, int lane) {
;     ...
;                 for (int q = 0; q < 4; ++q) { fa[q][s] = *(const mbf16x8*)(ap + (size_t)(16 * q) * K + kc + 32 * s); fb[q][s] = *(const mbf16x8*)(bp + (size_t)(16 * q) * K + kc + 32 * s); }
; #pragma unroll
;             for (int s = 0; s < 2; ++s)
; #pragma unroll
;                 for (int mi = 0; mi < 4; ++mi)
; #pragma unroll
;                     for (int ni = 0; ni < 4; ++ni) acc[mi][ni] = __builtin_amdgcn_mfma_f32_16x16x32_bf16(fa[mi][s], fb[ni][s], acc[mi][ni], 0, 0, 0);
;         }
; #pragma unroll
;         for (int ti = 0; ti < 16; ++ti) red[(wave * 16 + ti) * 64 + lane] = acc[ti >> 2][ti & 3];
;         __syncthreads();
; #pragma unroll
;         for (int q = 0; q < 2; ++q) { const int ti = 2 * wave + q, mi = ti >> 2, ni = ti & 3;
;             f32x4 s = red[ti * 64 + lane];
; #pragma unroll
;             for (int w = 1; w < 8; ++w) s += red[(w * 16 + ti) * 64 + lane];
;             const int c = n0 + 16 * ni + fr;
;             if (c < N) {
;                 const float gv = (MODE == 1) ? gate[c] : 1.f;
; #pragma unroll
;                 for (int i = 0; i < 4; ++i) { const int r = r0 + 16 * mi + 4 * fq + i; float v = s[i] * gv;
;                     if (act) { v = fmaxf(v, 0.f); v = v * v; } Ob[(size_t)r * ldo + c] = (u16)(pk2(v, 0.f) & 0xffffu); }
	v_mfma_f32_16x16x32_bf16 v[2:5], v[100:103], v[104:107], v[2:5]
	v_mfma_f32_16x16x32_bf16 v[6:9], v[100:103], v[108:111], v[6:9]
	v_mfma_f32_16x16x32_bf16 v[10:13], v[100:103], v[112:115], v[10:13]
	v_mfma_f32_16x16x32_bf16 v[14:17], v[100:103], v[116:119], v[14:17]
	s_waitcnt vmcnt(10)
	v_mfma_f32_16x16x32_bf16 v[18:21], v[200:203], v[104:107], v[18:21]
	v_mfma_f32_16x16x32_bf16 v[22:25], v[200:203], v[108:111], v[22:25]
	v_mfma_f32_16x16x32_bf16 v[26:29], v[200:203], v[112:115], v[26:29]
	v_mfma_f32_16x16x32_bf16 v[30:33], v[200:203], v[116:119], v[30:33]
	s_waitcnt vmcnt(9)
	v_mfma_f32_16x16x32_bf16 v[34:37], v[210:213], v[104:107], v[34:37]
	v_mfma_f32_16x16x32_bf16 v[38:41], v[210:213], v[108:111], v[38:41]
	v_mfma_f32_16x16x32_bf16 v[42:45], v[210:213], v[112:115], v[42:45]
	v_mfma_f32_16x16x32_bf16 v[46:49], v[210:213], v[116:119], v[46:49]
	s_waitcnt vmcnt(8)
	v_mfma_f32_16x16x32_bf16 v[50:53], v[226:229], v[104:107], v[50:53]
	v_mfma_f32_16x16x32_bf16 v[54:57], v[226:229], v[108:111], v[54:57]
	v_mfma_f32_16x16x32_bf16 v[62:65], v[226:229], v[112:115], v[62:65]
	v_mfma_f32_16x16x32_bf16 v[58:61], v[226:229], v[116:119], v[58:61]
	s_waitcnt vmcnt(3)
	v_mfma_f32_16x16x32_bf16 v[2:5], v[128:131], v[230:233], v[2:5]
	v_mfma_f32_16x16x32_bf16 v[6:9], v[128:131], v[234:237], v[6:9]
	v_mfma_f32_16x16x32_bf16 v[10:13], v[128:131], v[240:243], v[10:13]
	v_mfma_f32_16x16x32_bf16 v[14:17], v[128:131], v[244:247], v[14:17]
	s_waitcnt vmcnt(2)
	v_mfma_f32_16x16x32_bf16 v[18:21], v[124:127], v[230:233], v[18:21]
	v_mfma_f32_16x16x32_bf16 v[22:25], v[124:127], v[234:237], v[22:25]
	v_mfma_f32_16x16x32_bf16 v[26:29], v[124:127], v[240:243], v[26:29]
	v_mfma_f32_16x16x32_bf16 v[30:33], v[124:127], v[244:247], v[30:33]
	s_waitcnt vmcnt(1)
	v_mfma_f32_16x16x32_bf16 v[34:37], v[120:123], v[230:233], v[34:37]
	v_mfma_f32_16x16x32_bf16 v[38:41], v[120:123], v[234:237], v[38:41]
	v_mfma_f32_16x16x32_bf16 v[42:45], v[120:123], v[240:243], v[42:45]
	v_mfma_f32_16x16x32_bf16 v[46:49], v[120:123], v[244:247], v[46:49]
	s_waitcnt vmcnt(0)
	v_mfma_f32_16x16x32_bf16 v[50:53], v[136:139], v[230:233], v[50:53]
	v_mfma_f32_16x16x32_bf16 v[54:57], v[136:139], v[234:237], v[54:57]
	v_mfma_f32_16x16x32_bf16 v[62:65], v[136:139], v[240:243], v[62:65]
	v_mfma_f32_16x16x32_bf16 v[58:61], v[136:139], v[244:247], v[58:61]
	s_cbranch_scc0 .LBB0_383
	v_add_u32_e32 v0, s81, v85
	ds_write_b128 v0, v[2:5]
	ds_write_b128 v0, v[6:9] offset:1024
	ds_write_b128 v0, v[10:13] offset:2048
	ds_write_b128 v0, v[14:17] offset:3072
	ds_write_b128 v0, v[18:21] offset:4096
	ds_write_b128 v0, v[22:25] offset:5120
	ds_write_b128 v0, v[26:29] offset:6144
	ds_write_b128 v0, v[30:33] offset:7168
	ds_write_b128 v0, v[34:37] offset:8192
	ds_write_b128 v0, v[38:41] offset:9216
	ds_write_b128 v0, v[42:45] offset:10240
	ds_write_b128 v0, v[46:49] offset:11264
	ds_write_b128 v0, v[50:53] offset:12288
	ds_write_b128 v0, v[54:57] offset:13312
	ds_write_b128 v0, v[62:65] offset:14336
	ds_write_b128 v0, v[58:61] offset:15360
	v_add_u32_e32 v6, s77, v86
	v_or_b32_e32 v2, s85, v87
	v_cmp_gt_i32_e32 vcc, s76, v2
	v_or_b32_e32 v5, 1, v6
	v_or_b32_e32 v4, 2, v6
	v_or_b32_e32 v0, 3, v6
	s_waitcnt lgkmcnt(0)
	s_barrier
	s_and_saveexec_b64 s[44:45], vcc
	s_cbranch_execz .LBB0_386
	v_ashrrev_i32_e32 v3, 31, v2
	v_lshl_add_u64 v[8:9], v[2:3], 2, s[36:37]
	global_load_dword v7, v[8:9], off
	ds_read_b128 v[8:11], v88
	ds_read_b128 v[12:15], v88 offset:16384
	ds_read_b128 v[16:19], v88 offset:32768
	ds_read_b128 v[20:23], v88 offset:49152
	ds_read_b128 v[24:27], v89
	ds_read_b128 v[28:31], v90
	ds_read_b128 v[32:35], v91
	ds_read_b128 v[36:39], v92
	s_waitcnt lgkmcnt(6)
	v_pk_add_f32 v[8:9], v[8:9], v[12:13]
	v_pk_add_f32 v[10:11], v[10:11], v[14:15]
	s_waitcnt lgkmcnt(5)
	v_pk_add_f32 v[8:9], v[8:9], v[16:17]
	v_pk_add_f32 v[10:11], v[10:11], v[18:19]
	s_waitcnt lgkmcnt(4)
	v_pk_add_f32 v[8:9], v[8:9], v[20:21]
	v_pk_add_f32 v[10:11], v[10:11], v[22:23]
	s_waitcnt lgkmcnt(3)
	v_pk_add_f32 v[8:9], v[8:9], v[24:25]
	v_pk_add_f32 v[10:11], v[10:11], v[26:27]
	s_waitcnt lgkmcnt(2)
	v_pk_add_f32 v[8:9], v[8:9], v[28:29]
	v_pk_add_f32 v[10:11], v[10:11], v[30:31]
	s_waitcnt lgkmcnt(1)
	v_pk_add_f32 v[8:9], v[8:9], v[32:33]
	v_mad_i64_i32 v[40:41], s[46:47], v6, s76, 0
	s_waitcnt lgkmcnt(0)
	v_pk_add_f32 v[8:9], v[8:9], v[36:37]
	v_lshl_add_u64 v[2:3], v[2:3], 1, s[18:19]
	v_pk_add_f32 v[10:11], v[10:11], v[34:35]
	v_mad_i64_i32 v[42:43], s[46:47], v5, s76, 0
	v_mad_i64_i32 v[44:45], s[46:47], v4, s76, 0
	v_mad_i64_i32 v[46:47], s[46:47], v0, s76, 0
	v_lshl_add_u64 v[40:41], v[40:41], 1, v[2:3]
	v_pk_add_f32 v[10:11], v[10:11], v[38:39]
	v_lshl_add_u64 v[42:43], v[42:43], 1, v[2:3]
	v_lshl_add_u64 v[44:45], v[44:45], 1, v[2:3]
	v_lshl_add_u64 v[2:3], v[46:47], 1, v[2:3]
	s_waitcnt vmcnt(0)
	v_mul_f32_e32 v8, v7, v8
	v_cvt_pk_bf16_f32 v8, v8, v1
	v_mul_f32_e32 v9, v7, v9
	v_mul_f32_e32 v10, v7, v10
	v_mul_f32_e32 v7, v7, v11
	global_store_short v[40:41], v8, off
	v_cvt_pk_bf16_f32 v8, v9, v1
	global_store_short v[42:43], v8, off
	v_cvt_pk_bf16_f32 v8, v10, v1
	global_store_short v[44:45], v8, off
	v_cvt_pk_bf16_f32 v7, v7, v1
	global_store_short v[2:3], v7, off

; template <int MODE> __device__ __forceinline__ void mini_gemm_ctx(const u16* A, const u16* Bt, int N, int K, u16* Ob, int ldo, int act, const float* gate, LAS unsigned char* L, int vb, int G_, int wave, int lane) {
;     ...
;         const u16* ap = A + (size_t)(r0 + fr) * K + wave * kslice + 8 * fq; const u16* bp = Bt + (size_t)(n0 + fr) * K + wave * kslice + 8 * fq;
; #pragma unroll 1
;         for (int kc = 0; kc < kslice; kc += 64) {
;             mbf16x8 fa[4][2], fb[4][2];
; #pragma unroll
;             for (int s = 0; s < 2; ++s)
; #pragma unroll
;                 for (int q = 0; q < 4; ++q) { fa[q][s] = *(const mbf16x8*)(ap + (size_t)(16 * q) * K + kc + 32 * s); fb[q][s] = *(const mbf16x8*)(bp + (size_t)(16 * q) * K + kc + 32 * s); }
; #pragma unroll
;             for (int s = 0; s < 2; ++s)
; #pragma unroll
;                 for (int mi = 0; mi < 4; ++mi)
; #pragma unroll
;                     for (int ni = 0; ni < 4; ++ni) acc[mi][ni] = __builtin_amdgcn_mfma_f32_16x16x32_bf16(fa[mi][s], fb[ni][s], acc[mi][ni], 0, 0, 0);
;         }
.LBB0_394:
	v_lshl_add_u64 v[120:121], v[80:81], 0, v[66:67]
	v_lshl_add_u64 v[104:105], v[68:69], 0, v[66:67]
	v_lshl_add_u64 v[106:107], v[82:83], 0, v[66:67]
	v_lshl_add_u64 v[108:109], v[76:77], 0, v[66:67]
	v_lshl_add_u64 v[110:111], v[70:71], 0, v[66:67]
	v_add_co_u32_e32 v124, vcc, s2, v104
	v_add_co_u32_e64 v126, s[42:43], s2, v106
	v_add_co_u32_e64 v128, s[44:45], s2, v108
	v_add_co_u32_e64 v130, s[46:47], s2, v110
	v_addc_co_u32_e32 v125, vcc, 0, v105, vcc
	v_addc_co_u32_e64 v127, vcc, 0, v107, s[42:43]
	v_addc_co_u32_e64 v129, vcc, 0, v109, s[44:45]
	v_addc_co_u32_e64 v131, vcc, 0, v111, s[46:47]
	v_lshl_add_u64 v[122:123], v[72:73], 0, v[66:67]
	v_lshl_add_u64 v[132:133], v[74:75], 0, v[66:67]
	v_lshl_add_u64 v[134:135], v[78:79], 0, v[66:67]
	global_load_dwordx4 v[136:139], v[120:121], off offset:-64
	global_load_dwordx4 v[140:143], v[124:125], off
	global_load_dwordx4 v[144:147], v[126:127], off
	global_load_dwordx4 v[148:151], v[128:129], off
	global_load_dwordx4 v[152:155], v[130:131], off
	global_load_dwordx4 v[156:159], v[122:123], off
	global_load_dwordx4 v[160:163], v[132:133], off
	global_load_dwordx4 v[164:167], v[134:135], off
	global_load_dwordx4 v[168:171], v[120:121], off
	global_load_dwordx4 v[172:175], v[124:125], off offset:64
	global_load_dwordx4 v[176:179], v[126:127], off offset:64
	global_load_dwordx4 v[180:183], v[128:129], off offset:64
	global_load_dwordx4 v[184:187], v[130:131], off offset:64
	global_load_dwordx4 v[188:191], v[122:123], off offset:64
	global_load_dwordx4 v[192:195], v[132:133], off offset:64
	global_load_dwordx4 v[196:199], v[134:135], off offset:64
	global_load_dwordx4 v[100:103], v[120:121], off offset:64
	global_load_dwordx4 v[104:107], v[124:125], off offset:128
	global_load_dwordx4 v[108:111], v[126:127], off offset:128
	global_load_dwordx4 v[112:115], v[128:129], off offset:128
	global_load_dwordx4 v[116:119], v[130:131], off offset:128
	global_load_dwordx4 v[200:203], v[122:123], off offset:128
	global_load_dwordx4 v[210:213], v[132:133], off offset:128
	global_load_dwordx4 v[226:229], v[134:135], off offset:128
	global_load_dwordx4 v[230:233], v[124:125], off offset:192
	global_load_dwordx4 v[234:237], v[126:127], off offset:192
	global_load_dwordx4 v[240:243], v[128:129], off offset:192
	global_load_dwordx4 v[244:247], v[130:131], off offset:192
	global_load_dwordx4 v[128:131], v[120:121], off offset:128
	global_load_dwordx4 v[124:127], v[122:123], off offset:192
	global_load_dwordx4 v[120:123], v[132:133], off offset:192
	s_add_i32 s73, s73, 128
	s_lshl_b64 s[100:101], s[24:25], 1
	v_lshl_add_u64 v[68:69], v[68:69], 0, s[100:101]
	v_lshl_add_u64 v[70:71], v[70:71], 0, s[100:101]
	v_lshl_add_u64 v[72:73], v[72:73], 0, s[100:101]
	v_lshl_add_u64 v[74:75], v[74:75], 0, s[100:101]
	v_lshl_add_u64 v[76:77], v[76:77], 0, s[100:101]
	v_lshl_add_u64 v[78:79], v[78:79], 0, s[100:101]
	v_lshl_add_u64 v[80:81], v[80:81], 0, s[100:101]
	v_lshl_add_u64 v[82:83], v[82:83], 0, s[100:101]
	s_cmp_ge_u32 s73, s80
	s_waitcnt vmcnt(26)
	v_mfma_f32_16x16x32_bf16 v[2:5], v[136:139], v[140:143], v[2:5]
	v_mfma_f32_16x16x32_bf16 v[6:9], v[136:139], v[144:147], v[6:9]
	v_mfma_f32_16x16x32_bf16 v[10:13], v[136:139], v[148:151], v[10:13]
	v_mfma_f32_16x16x32_bf16 v[14:17], v[136:139], v[152:155], v[14:17]
	global_load_dwordx4 v[136:139], v[134:135], off offset:192
	s_waitcnt vmcnt(26)
	v_mfma_f32_16x16x32_bf16 v[18:21], v[156:159], v[140:143], v[18:21]
	v_mfma_f32_16x16x32_bf16 v[22:25], v[156:159], v[144:147], v[22:25]
	v_mfma_f32_16x16x32_bf16 v[26:29], v[156:159], v[148:151], v[26:29]
	v_mfma_f32_16x16x32_bf16 v[30:33], v[156:159], v[152:155], v[30:33]
	s_waitcnt vmcnt(25)
	v_mfma_f32_16x16x32_bf16 v[34:37], v[160:163], v[140:143], v[34:37]
	v_mfma_f32_16x16x32_bf16 v[38:41], v[160:163], v[144:147], v[38:41]
	v_mfma_f32_16x16x32_bf16 v[42:45], v[160:163], v[148:151], v[42:45]
	v_mfma_f32_16x16x32_bf16 v[46:49], v[160:163], v[152:155], v[46:49]
	s_waitcnt vmcnt(24)
	v_mfma_f32_16x16x32_bf16 v[50:53], v[164:167], v[140:143], v[50:53]
	v_mfma_f32_16x16x32_bf16 v[54:57], v[164:167], v[144:147], v[54:57]
	v_mfma_f32_16x16x32_bf16 v[62:65], v[164:167], v[148:151], v[62:65]
	v_mfma_f32_16x16x32_bf16 v[58:61], v[164:167], v[152:155], v[58:61]
	s_waitcnt vmcnt(19)
	v_mfma_f32_16x16x32_bf16 v[2:5], v[168:171], v[172:175], v[2:5]
	v_mfma_f32_16x16x32_bf16 v[6:9], v[168:171], v[176:179], v[6:9]
	v_mfma_f32_16x16x32_bf16 v[10:13], v[168:171], v[180:183], v[10:13]
	v_mfma_f32_16x16x32_bf16 v[14:17], v[168:171], v[184:187], v[14:17]
	s_waitcnt vmcnt(18)
	v_mfma_f32_16x16x32_bf16 v[18:21], v[188:191], v[172:175], v[18:21]
	v_mfma_f32_16x16x32_bf16 v[22:25], v[188:191], v[176:179], v[22:25]
	v_mfma_f32_16x16x32_bf16 v[26:29], v[188:191], v[180:183], v[26:29]
	v_mfma_f32_16x16x32_bf16 v[30:33], v[188:191], v[184:187], v[30:33]
	s_waitcnt vmcnt(17)
	v_mfma_f32_16x16x32_bf16 v[34:37], v[192:195], v[172:175], v[34:37]
	v_mfma_f32_16x16x32_bf16 v[38:41], v[192:195], v[176:179], v[38:41]
	v_mfma_f32_16x16x32_bf16 v[42:45], v[192:195], v[180:183], v[42:45]
	v_mfma_f32_16x16x32_bf16 v[46:49], v[192:195], v[184:187], v[46:49]
	s_waitcnt vmcnt(16)
	v_mfma_f32_16x16x32_bf16 v[50:53], v[196:199], v[172:175], v[50:53]
	v_mfma_f32_16x16x32_bf16 v[54:57], v[196:199], v[176:179], v[54:57]
	v_mfma_f32_16x16x32_bf16 v[62:65], v[196:199], v[180:183], v[62:65]
	v_mfma_f32_16x16x32_bf16 v[58:61], v[196:199], v[184:187], v[58:61]
	s_waitcnt vmcnt(11)
; __device__ __forceinline__ unsigned pk2(float lo, float hi) { return pg8::cvt_pk_bf16(lo, hi); }
; template <int MODE> __device__ __forceinline__ void mini_gemm_ctx(const u16* A, const u16* Bt, int N, int K, u16* Ob, int ldo, int act, const float* gate, LAS unsigned char* L, int vb, int G_, int wave, int lane) {
;     ...
;                 for (int q = 0; q < 4; ++q) { fa[q][s] = *(const mbf16x8*)(ap + (size_t)(16 * q) * K + kc + 32 * s); fb[q][s] = *(const mbf16x8*)(bp + (size_t)(16 * q) * K + kc + 32 * s); }
; #pragma unroll
;             for (int s = 0; s < 2; ++s)
; #pragma unroll
;                 for (int mi = 0; mi < 4; ++mi)
; #pragma unroll
;                     for (int ni = 0; ni < 4; ++ni) acc[mi][ni] = __builtin_amdgcn_mfma_f32_16x16x32_bf16(fa[mi][s], fb[ni][s], acc[mi][ni], 0, 0, 0);
;         }
; #pragma unroll
;         for (int ti = 0; ti < 16; ++ti) red[(wave * 16 + ti) * 64 + lane] = acc[ti >> 2][ti & 3];
;         __syncthreads();
; #pragma unroll
;         for (int q = 0; q < 2; ++q) { const int ti = 2 * wave + q, mi = ti >> 2, ni = ti & 3;
;             f32x4 s = red[ti * 64 + lane];
; #pragma unroll
;             for (int w = 1; w < 8; ++w) s += red[(w * 16 + ti) * 64 + lane];
;             const int c = n0 + 16 * ni + fr;
;             if (c < N) {
;                 const float gv = (MODE == 1) ? gate[c] : 1.f;
; #pragma unroll
;                 for (int i = 0; i < 4; ++i) { const int r = r0 + 16 * mi + 4 * fq + i; float v = s[i] * gv;
;                     if (act) { v = fmaxf(v, 0.f); v = v * v; } Ob[(size_t)r * ldo + c] = (u16)(pk2(v, 0.f) & 0xffffu); }
	v_mfma_f32_16x16x32_bf16 v[2:5], v[100:103], v[104:107], v[2:5]
	v_mfma_f32_16x16x32_bf16 v[6:9], v[100:103], v[108:111], v[6:9]
	v_mfma_f32_16x16x32_bf16 v[10:13], v[100:103], v[112:115], v[10:13]
	v_mfma_f32_16x16x32_bf16 v[14:17], v[100:103], v[116:119], v[14:17]
	s_waitcnt vmcnt(10)
	v_mfma_f32_16x16x32_bf16 v[18:21], v[200:203], v[104:107], v[18:21]
	v_mfma_f32_16x16x32_bf16 v[22:25], v[200:203], v[108:111], v[22:25]
	v_mfma_f32_16x16x32_bf16 v[26:29], v[200:203], v[112:115], v[26:29]
	v_mfma_f32_16x16x32_bf16 v[30:33], v[200:203], v[116:119], v[30:33]
	s_waitcnt vmcnt(9)
	v_mfma_f32_16x16x32_bf16 v[34:37], v[210:213], v[104:107], v[34:37]
	v_mfma_f32_16x16x32_bf16 v[38:41], v[210:213], v[108:111], v[38:41]
	v_mfma_f32_16x16x32_bf16 v[42:45], v[210:213], v[112:115], v[42:45]
	v_mfma_f32_16x16x32_bf16 v[46:49], v[210:213], v[116:119], v[46:49]
	s_waitcnt vmcnt(8)
	v_mfma_f32_16x16x32_bf16 v[50:53], v[226:229], v[104:107], v[50:53]
	v_mfma_f32_16x16x32_bf16 v[54:57], v[226:229], v[108:111], v[54:57]
	v_mfma_f32_16x16x32_bf16 v[62:65], v[226:229], v[112:115], v[62:65]
	v_mfma_f32_16x16x32_bf16 v[58:61], v[226:229], v[116:119], v[58:61]
	s_waitcnt vmcnt(3)
	v_mfma_f32_16x16x32_bf16 v[2:5], v[128:131], v[230:233], v[2:5]
	v_mfma_f32_16x16x32_bf16 v[6:9], v[128:131], v[234:237], v[6:9]
	v_mfma_f32_16x16x32_bf16 v[10:13], v[128:131], v[240:243], v[10:13]
	v_mfma_f32_16x16x32_bf16 v[14:17], v[128:131], v[244:247], v[14:17]
	s_waitcnt vmcnt(2)
	v_mfma_f32_16x16x32_bf16 v[18:21], v[124:127], v[230:233], v[18:21]
	v_mfma_f32_16x16x32_bf16 v[22:25], v[124:127], v[234:237], v[22:25]
	v_mfma_f32_16x16x32_bf16 v[26:29], v[124:127], v[240:243], v[26:29]
	v_mfma_f32_16x16x32_bf16 v[30:33], v[124:127], v[244:247], v[30:33]
	s_waitcnt vmcnt(1)
	v_mfma_f32_16x16x32_bf16 v[34:37], v[120:123], v[230:233], v[34:37]
	v_mfma_f32_16x16x32_bf16 v[38:41], v[120:123], v[234:237], v[38:41]
	v_mfma_f32_16x16x32_bf16 v[42:45], v[120:123], v[240:243], v[42:45]
	v_mfma_f32_16x16x32_bf16 v[46:49], v[120:123], v[244:247], v[46:49]
	s_waitcnt vmcnt(0)
	v_mfma_f32_16x16x32_bf16 v[50:53], v[136:139], v[230:233], v[50:53]
	v_mfma_f32_16x16x32_bf16 v[54:57], v[136:139], v[234:237], v[54:57]
	v_mfma_f32_16x16x32_bf16 v[62:65], v[136:139], v[240:243], v[62:65]
	v_mfma_f32_16x16x32_bf16 v[58:61], v[136:139], v[244:247], v[58:61]
	s_cbranch_scc0 .LBB0_394
	v_add_u32_e32 v0, s81, v85
	ds_write_b128 v0, v[2:5]
	ds_write_b128 v0, v[6:9] offset:1024
	ds_write_b128 v0, v[10:13] offset:2048
	ds_write_b128 v0, v[14:17] offset:3072
	ds_write_b128 v0, v[18:21] offset:4096
	ds_write_b128 v0, v[22:25] offset:5120
	ds_write_b128 v0, v[26:29] offset:6144
	ds_write_b128 v0, v[30:33] offset:7168
	ds_write_b128 v0, v[34:37] offset:8192
	ds_write_b128 v0, v[38:41] offset:9216
	ds_write_b128 v0, v[42:45] offset:10240
	ds_write_b128 v0, v[46:49] offset:11264
	ds_write_b128 v0, v[50:53] offset:12288
	ds_write_b128 v0, v[54:57] offset:13312
	ds_write_b128 v0, v[62:65] offset:14336
	ds_write_b128 v0, v[58:61] offset:15360
	v_add_u32_e32 v6, s72, v86
	v_or_b32_e32 v2, s63, v87
	v_cmp_gt_i32_e32 vcc, s76, v2
	v_or_b32_e32 v5, 1, v6
	v_or_b32_e32 v4, 2, v6
	v_or_b32_e32 v0, 3, v6
	s_waitcnt lgkmcnt(0)
	s_barrier
	s_and_saveexec_b64 s[42:43], vcc
	s_cbranch_execz .LBB0_397
	ds_read_b128 v[8:11], v88
	ds_read_b128 v[12:15], v88 offset:16384
	ds_read_b128 v[16:19], v88 offset:32768
	ds_read_b128 v[20:23], v88 offset:49152
	v_ashrrev_i32_e32 v3, 31, v2
	v_lshl_add_u64 v[2:3], v[2:3], 1, s[18:19]
	s_waitcnt lgkmcnt(2)
	v_pk_add_f32 v[10:11], v[10:11], v[14:15]
	v_pk_add_f32 v[12:13], v[8:9], v[12:13]
	s_waitcnt lgkmcnt(1)
	v_pk_add_f32 v[14:15], v[10:11], v[18:19]
	ds_read_b128 v[8:11], v89
	v_pk_add_f32 v[12:13], v[12:13], v[16:17]
	s_waitcnt lgkmcnt(1)
	v_pk_add_f32 v[16:17], v[14:15], v[22:23]
	v_pk_add_f32 v[20:21], v[12:13], v[20:21]
	ds_read_b128 v[12:15], v90
	s_waitcnt lgkmcnt(1)
	v_pk_add_f32 v[22:23], v[16:17], v[10:11]
	ds_read_b128 v[16:19], v91
	v_pk_add_f32 v[20:21], v[20:21], v[8:9]
	ds_read_b128 v[8:11], v92
	s_waitcnt lgkmcnt(2)
	v_pk_add_f32 v[12:13], v[20:21], v[12:13]
	v_pk_add_f32 v[14:15], v[22:23], v[14:15]
	s_waitcnt lgkmcnt(1)
	v_pk_add_f32 v[12:13], v[12:13], v[16:17]
	v_pk_add_f32 v[14:15], v[14:15], v[18:19]
	s_waitcnt lgkmcnt(0)
	v_pk_add_f32 v[8:9], v[12:13], v[8:9]
	v_mad_i64_i32 v[12:13], s[44:45], v6, s76, 0
	v_max_f32_e32 v7, 0, v8
	v_mul_f32_e32 v7, v7, v7
	v_cndmask_b32_e64 v7, v8, v7, s[38:39]
	v_cvt_pk_bf16_f32 v7, v7, v1
	v_lshl_add_u64 v[12:13], v[12:13], 1, v[2:3]
	global_store_short v[12:13], v7, off
	v_max_f32_e32 v7, 0, v9
	v_mul_f32_e32 v7, v7, v7
	v_cndmask_b32_e64 v7, v9, v7, s[38:39]
	v_mad_i64_i32 v[8:9], s[44:45], v5, s76, 0
	v_pk_add_f32 v[10:11], v[14:15], v[10:11]
	v_cvt_pk_bf16_f32 v7, v7, v1
	v_lshl_add_u64 v[8:9], v[8:9], 1, v[2:3]
	global_store_short v[8:9], v7, off
	v_max_f32_e32 v7, 0, v10
	v_mul_f32_e32 v7, v7, v7
	v_cndmask_b32_e64 v7, v10, v7, s[38:39]
	v_mad_i64_i32 v[8:9], s[44:45], v4, s76, 0
	v_cvt_pk_bf16_f32 v7, v7, v1
	v_lshl_add_u64 v[8:9], v[8:9], 1, v[2:3]
	global_store_short v[8:9], v7, off
	v_max_f32_e32 v7, 0, v11
	v_mul_f32_e32 v7, v7, v7
	v_mad_i64_i32 v[8:9], s[44:45], v0, s76, 0
	v_cndmask_b32_e64 v7, v11, v7, s[38:39]
	v_lshl_add_u64 v[2:3], v[8:9], 1, v[2:3]
	v_cvt_pk_bf16_f32 v7, v7, v1
	global_store_short v[2:3], v7, off
